# stacked latency trims on v085: prologue first-QK reads together, exact vmcnt(5) row-pass waits, mode-0 epilogue subw loads up-front
# baseline (speedup 1.0000x reference)
.LBB0_679:
	s_cmpk_gt_u32 s18, 0xff
	s_waitcnt lgkmcnt(0)
	s_barrier
	s_cbranch_scc1 .LBB0_634
	ds_read2st64_b32 v[30:31], v1 offset1:1
	ds_read2st64_b32 v[32:33], v1 offset0:2 offset1:3
	ds_read2st64_b32 v[44:45], v1 offset0:4 offset1:5
	ds_read2st64_b32 v[46:47], v1 offset0:6 offset1:7
	ds_read2st64_b32 v[48:49], v1 offset0:8 offset1:9
	ds_read2st64_b32 v[50:51], v1 offset0:10 offset1:11
	ds_read2st64_b32 v[52:53], v1 offset0:12 offset1:13
	ds_read2st64_b32 v[26:27], v1 offset0:14 offset1:15
	ds_read2st64_b32 v[54:55], v1 offset0:24 offset1:25
	ds_read2st64_b32 v[56:57], v1 offset0:26 offset1:27
	ds_read2st64_b32 v[58:59], v1 offset0:28 offset1:29
	ds_read2st64_b32 v[28:29], v1 offset0:30 offset1:31
	ds_read2st64_b32 v[60:61], v1 offset0:16 offset1:17
	ds_read2st64_b32 v[62:63], v1 offset0:18 offset1:19
	ds_read2st64_b32 v[64:65], v1 offset0:20 offset1:21
	ds_read2st64_b32 v[66:67], v1 offset0:22 offset1:23
	s_waitcnt lgkmcnt(4)
	v_pk_fma_f32 v[70:71], v[192:193], v[28:29], v[16:17] neg_lo:[1,0,0] neg_hi:[1,0,0]
	v_pk_fma_f32 v[68:69], v[192:193], v[26:27], v[14:15] neg_lo:[1,0,0] neg_hi:[1,0,0]
	v_pk_mul_f32 v[14:15], v[70:71], v[70:71]
	s_waitcnt lgkmcnt(3)
	v_pk_fma_f32 v[40:41], v[192:193], v[60:61], v[40:41] neg_lo:[1,0,0] neg_hi:[1,0,0]
	v_pk_fma_f32 v[72:73], v[68:69], v[68:69], v[14:15]
	global_load_dwordx4 v[14:17], v162, s[84:85]
	global_load_dwordx4 v[26:29], v162, s[84:85] offset:128
	global_load_dwordx4 v[110:113], v162, s[84:85] offset:32
	global_load_dwordx4 v[114:117], v162, s[84:85] offset:160
	global_load_dwordx4 v[118:121], v162, s[84:85] offset:64
	global_load_dwordx4 v[122:125], v162, s[84:85] offset:192
	global_load_dwordx4 v[126:129], v162, s[84:85] offset:96
	global_load_dwordx4 v[98:101], v162, s[84:85] offset:224
	s_waitcnt lgkmcnt(2)
	v_pk_fma_f32 v[42:43], v[192:193], v[62:63], v[42:43] neg_lo:[1,0,0] neg_hi:[1,0,0]
	v_pk_mul_f32 v[60:61], v[40:41], v[40:41]
	v_pk_fma_f32 v[30:31], v[192:193], v[30:31], v[36:37] neg_lo:[1,0,0] neg_hi:[1,0,0]
	v_pk_mul_f32 v[62:63], v[42:43], v[42:43]
	v_pk_fma_f32 v[32:33], v[192:193], v[32:33], v[38:39] neg_lo:[1,0,0] neg_hi:[1,0,0]
	v_pk_fma_f32 v[36:37], v[30:31], v[30:31], v[60:61]
	v_pk_fma_f32 v[38:39], v[32:33], v[32:33], v[62:63]
	v_pk_add_f32 v[36:37], v[36:37], v[36:37] op_sel:[0,1] op_sel_hi:[1,0]
	s_waitcnt lgkmcnt(1)
	v_pk_fma_f32 v[22:23], v[192:193], v[64:65], v[22:23] neg_lo:[1,0,0] neg_hi:[1,0,0]
	v_pk_add_f32 v[36:37], v[36:37], v[38:39]
	v_pk_mul_f32 v[60:61], v[22:23], v[22:23]
	v_pk_fma_f32 v[18:19], v[192:193], v[44:45], v[18:19] neg_lo:[1,0,0] neg_hi:[1,0,0]
	v_pk_add_f32 v[36:37], v[36:37], v[38:39] op_sel:[0,1] op_sel_hi:[1,0]
	s_waitcnt lgkmcnt(0)
	v_pk_fma_f32 v[24:25], v[192:193], v[66:67], v[24:25] neg_lo:[1,0,0] neg_hi:[1,0,0]
	v_pk_fma_f32 v[44:45], v[18:19], v[18:19], v[60:61]
	v_pk_mul_f32 v[38:39], v[24:25], v[24:25]
	v_pk_fma_f32 v[20:21], v[192:193], v[46:47], v[20:21] neg_lo:[1,0,0] neg_hi:[1,0,0]
	v_pk_add_f32 v[36:37], v[36:37], v[44:45]
	v_pk_fma_f32 v[38:39], v[20:21], v[20:21], v[38:39]
	v_pk_add_f32 v[36:37], v[36:37], v[44:45] op_sel:[0,1] op_sel_hi:[1,0]
	v_pk_fma_f32 v[12:13], v[192:193], v[56:57], v[12:13] neg_lo:[1,0,0] neg_hi:[1,0,0]
	v_pk_add_f32 v[36:37], v[36:37], v[38:39]
	v_pk_fma_f32 v[10:11], v[192:193], v[54:55], v[10:11] neg_lo:[1,0,0] neg_hi:[1,0,0]
	v_pk_add_f32 v[36:37], v[36:37], v[38:39] op_sel:[0,1] op_sel_hi:[1,0]
	v_pk_mul_f32 v[38:39], v[12:13], v[12:13]
	v_pk_fma_f32 v[46:47], v[192:193], v[50:51], v[8:9] neg_lo:[1,0,0] neg_hi:[1,0,0]
	v_pk_mul_f32 v[44:45], v[10:11], v[10:11]
	v_pk_fma_f32 v[8:9], v[46:47], v[46:47], v[38:39]
	v_pk_fma_f32 v[38:39], v[192:193], v[48:49], v[2:3] neg_lo:[1,0,0] neg_hi:[1,0,0]
	v_lshlrev_b64 v[34:35], 11, v[34:35]
	v_pk_fma_f32 v[2:3], v[38:39], v[38:39], v[44:45]
	v_pk_fma_f32 v[44:45], v[192:193], v[52:53], v[4:5] neg_lo:[1,0,0] neg_hi:[1,0,0]
	v_pk_add_f32 v[36:37], v[36:37], v[2:3]
	s_lshl_b32 s92, s74, 7
	v_pk_add_f32 v[2:3], v[36:37], v[2:3] op_sel:[0,1] op_sel_hi:[1,0]
	v_pk_fma_f32 v[36:37], v[192:193], v[58:59], v[6:7] neg_lo:[1,0,0] neg_hi:[1,0,0]
	v_pk_add_f32 v[2:3], v[2:3], v[8:9]
	v_pk_mul_f32 v[6:7], v[36:37], v[36:37]
	v_pk_add_f32 v[2:3], v[2:3], v[8:9] op_sel:[0,1] op_sel_hi:[1,0]
	v_pk_fma_f32 v[4:5], v[44:45], v[44:45], v[6:7]
	s_nop 0
	v_pk_add_f32 v[2:3], v[2:3], v[4:5]
	s_nop 0
	v_pk_add_f32 v[2:3], v[2:3], v[4:5] op_sel:[0,1] op_sel_hi:[1,0]
	s_nop 0
	v_pk_add_f32 v[2:3], v[2:3], v[72:73]
	s_nop 0
	v_pk_add_f32 v[2:3], v[2:3], v[72:73] op_sel:[0,1] op_sel_hi:[1,0]
	s_nop 0
	v_mov_b32_e32 v1, v2
	s_nop 1
	v_permlane32_swap_b32_e32 v2, v1
	v_add_f32_e32 v1, v2, v1
	v_fmamk_f32 v1, v1, 0x3c800000, v228
	v_mul_f32_e32 v2, 0x4f800000, v1
	v_cmp_gt_f32_e32 vcc, s49, v1
	s_nop 1
	v_cndmask_b32_e32 v1, v1, v2, vcc
	v_sqrt_f32_e32 v4, v1
	v_lshl_add_u64 v[2:3], s[8:9], 0, v[34:35]
	v_lshl_add_u64 v[2:3], v[2:3], 0, s[92:93]
	v_add_u32_e32 v5, -1, v4
	v_fma_f32 v6, -v5, v4, v1
	v_cmp_ge_f32_e64 s[0:1], 0, v6
	v_add_u32_e32 v6, 1, v4
	s_nop 0
	v_cndmask_b32_e64 v5, v4, v5, s[0:1]
	v_fma_f32 v4, -v6, v4, v1
	v_cmp_lt_f32_e64 s[0:1], 0, v4
	s_nop 1
	v_cndmask_b32_e64 v4, v5, v6, s[0:1]
	v_mul_f32_e32 v5, 0x37800000, v4
	v_cndmask_b32_e32 v4, v4, v5, vcc
	v_cmp_class_f32_e32 vcc, v1, v229
	v_mov_b32_e32 v5, v0
	s_nop 0
	v_cndmask_b32_e32 v1, v4, v1, vcc
	v_div_scale_f32 v6, s[0:1], v1, v1, v234
	v_rcp_f32_e32 v7, v6
	v_lshlrev_b32_e32 v4, 3, v180
	v_lshl_add_u64 v[34:35], v[2:3], 0, v[4:5]
	v_fma_f32 v2, -v6, v7, 1.0
	v_fmac_f32_e32 v7, v2, v7
	v_div_scale_f32 v2, vcc, v234, v1, v234
	v_mul_f32_e32 v3, v2, v7
	v_fma_f32 v4, -v6, v3, v2
	v_fmac_f32_e32 v3, v4, v7
	v_fma_f32 v2, -v6, v3, v2
	v_div_fmas_f32 v2, v2, v7, v3
	v_div_fixup_f32 v48, v2, v1, v234
	v_pk_mul_f32 v[2:3], v[30:31], v[48:49] op_sel_hi:[1,0]
	v_pk_mul_f32 v[4:5], v[32:33], v[48:49] op_sel_hi:[1,0]
	s_waitcnt vmcnt(0)
	v_pk_mul_f32 v[2:3], v[14:15], v[2:3]
	v_pk_mul_f32 v[4:5], v[16:17], v[4:5]
	v_cvt_pk_bf16_f32 v2, v2, v3
	v_cvt_pk_bf16_f32 v3, v4, v5
	v_pk_mul_f32 v[4:5], v[40:41], v[48:49] op_sel_hi:[1,0]
	v_pk_mul_f32 v[6:7], v[42:43], v[48:49] op_sel_hi:[1,0]
	s_waitcnt vmcnt(0)
	v_pk_mul_f32 v[4:5], v[26:27], v[4:5]
	v_pk_mul_f32 v[6:7], v[28:29], v[6:7]
	v_cvt_pk_bf16_f32 v4, v4, v5
	v_cvt_pk_bf16_f32 v5, v6, v7
	global_store_dwordx2 v[34:35], v[2:3], off
	global_store_dwordx2 v[34:35], v[4:5], off offset:64
	v_pk_mul_f32 v[14:15], v[18:19], v[48:49] op_sel_hi:[1,0]
	v_pk_mul_f32 v[16:17], v[20:21], v[48:49] op_sel_hi:[1,0]
	v_pk_mul_f32 v[18:19], v[22:23], v[48:49] op_sel_hi:[1,0]
	v_pk_mul_f32 v[20:21], v[24:25], v[48:49] op_sel_hi:[1,0]
	v_pk_mul_f32 v[10:11], v[10:11], v[48:49] op_sel_hi:[1,0]
	v_pk_mul_f32 v[12:13], v[12:13], v[48:49] op_sel_hi:[1,0]
	v_pk_mul_f32 v[2:3], v[110:111], v[14:15]
	v_pk_mul_f32 v[4:5], v[112:113], v[16:17]
	v_pk_mul_f32 v[6:7], v[114:115], v[18:19]
	v_pk_mul_f32 v[8:9], v[116:117], v[20:21]
	v_cvt_pk_bf16_f32 v2, v2, v3
	v_cvt_pk_bf16_f32 v3, v4, v5
	v_cvt_pk_bf16_f32 v4, v6, v7
	v_cvt_pk_bf16_f32 v5, v8, v9
	global_store_dwordx2 v[34:35], v[2:3], off offset:16
	global_store_dwordx2 v[34:35], v[4:5], off offset:80
	v_pk_mul_f32 v[14:15], v[38:39], v[48:49] op_sel_hi:[1,0]
	v_pk_mul_f32 v[16:17], v[46:47], v[48:49] op_sel_hi:[1,0]
	v_pk_mul_f32 v[2:3], v[14:15], v[118:119]
	v_pk_mul_f32 v[4:5], v[16:17], v[120:121]
	v_pk_mul_f32 v[6:7], v[10:11], v[122:123]
	v_pk_mul_f32 v[8:9], v[12:13], v[124:125]
	v_cvt_pk_bf16_f32 v2, v2, v3
	v_cvt_pk_bf16_f32 v3, v4, v5
	v_cvt_pk_bf16_f32 v4, v6, v7
	v_cvt_pk_bf16_f32 v5, v8, v9
	global_store_dwordx2 v[34:35], v[2:3], off offset:32
	global_store_dwordx2 v[34:35], v[4:5], off offset:96
	v_pk_mul_f32 v[10:11], v[44:45], v[48:49] op_sel_hi:[1,0]
	v_pk_mul_f32 v[12:13], v[68:69], v[48:49] op_sel_hi:[1,0]
	v_pk_mul_f32 v[14:15], v[36:37], v[48:49] op_sel_hi:[1,0]
	v_pk_mul_f32 v[16:17], v[70:71], v[48:49] op_sel_hi:[1,0]
	v_pk_mul_f32 v[2:3], v[10:11], v[126:127]
	v_pk_mul_f32 v[4:5], v[12:13], v[128:129]
	v_pk_mul_f32 v[6:7], v[14:15], v[98:99]
	v_pk_mul_f32 v[8:9], v[16:17], v[100:101]
	v_cvt_pk_bf16_f32 v2, v2, v3
	v_cvt_pk_bf16_f32 v3, v4, v5
	v_cvt_pk_bf16_f32 v4, v6, v7
	v_cvt_pk_bf16_f32 v5, v8, v9
	global_store_dwordx2 v[34:35], v[2:3], off offset:48
	global_store_dwordx2 v[34:35], v[4:5], off offset:112
	s_branch .LBB0_634
